# W_in conversion loop rewritten: 4 output rows x 8-wide k chunk per lane, 8 dwordx4 loads in flight, full 128B lines read and written per wave
# speedup vs baseline: 1.0077x; 1.0046x over previous
.LBB0_626:
	s_or_b64 exec, exec, s[10:11]
	s_and_b64 vcc, exec, s[6:7]
	s_cbranch_vccz .LBB0_667
	v_readlane_b32 s0, v254, 7
	v_readlane_b32 s1, v254, 8
	s_waitcnt vmcnt(0)
	v_lshl_add_u32 v6, s0, 8, v176
	s_mov_b32 s0, 0x62000
	v_cmp_gt_i32_e32 vcc, s0, v6
	s_and_saveexec_b64 s[0:1], vcc
	s_cbranch_execz .LBB0_666
	v_readlane_b32 s4, v254, 19
	s_mul_hi_i32 s2, s4, 0x3090000
	s_mul_i32 s4, s4, 0x3090000
	s_add_u32 s4, s72, s4
	s_addc_u32 s5, s73, s2
	v_readlane_b32 s6, v254, 11
	v_readlane_b32 s8, v254, 9
	v_readlane_b32 s7, v254, 12
	s_add_u32 s6, s6, 0x12cb1000
	v_readlane_b32 s9, v254, 10
	s_addc_u32 s7, s7, 0
	s_lshl_b32 s2, s8, 8
	s_mov_b64 s[8:9], 0
	s_branch .LBB0_630
.LBB0_630:
	v_lshrrev_b32_e32 v0, 6, v6
	s_mov_b32 s10, 0x539782a
	v_lshrrev_b32_e32 v1, 3, v0
	v_mul_hi_u32 v1, v1, s10
	v_mul_u32_u24_e32 v3, 0x188, v1
	v_sub_u32_e32 v0, v0, v3
	v_and_b32_e32 v3, 7, v6
	v_lshlrev_b32_e32 v3, 2, v3
	v_lshl_or_b32 v0, v0, 5, v3
	v_bfe_u32 v3, v6, 3, 3
	v_lshl_or_b32 v1, v1, 3, v3
	s_movk_i32 s10, 0x87f
	v_cmp_lt_u32_e64 s[12:13], s10, v0
	s_movk_i32 s10, 0xc7f
	v_cmp_lt_u32_e64 s[14:15], s10, v0
	s_movk_i32 s10, 0x18ff
	v_cmp_lt_u32_e64 s[34:35], s10, v0
	s_movk_i32 s10, 0x1cff
	v_cmp_lt_u32_e64 s[36:37], s10, v0
	s_movk_i32 s10, 0x20ff
	v_cmp_lt_u32_e64 s[38:39], s10, v0
	v_mov_b32_e32 v2, 0
	v_mov_b32_e32 v3, 0x390
	v_cndmask_b32_e64 v2, v2, v3, s[12:13]
	v_mov_b32_e32 v3, 0x790
	v_cndmask_b32_e64 v2, v2, v3, s[14:15]
	v_mov_b32_e32 v3, 0xffffef10
	v_cndmask_b32_e64 v2, v2, v3, s[34:35]
	v_mov_b32_e32 v3, 0xfffff310
	v_cndmask_b32_e64 v2, v2, v3, s[36:37]
	v_mov_b32_e32 v3, 0xffffff90
	v_cndmask_b32_e64 v2, v2, v3, s[38:39]
	v_add_u32_e32 v2, v0, v2
	v_subrev_u32_e32 v3, 0x810, v0
	s_movk_i32 s10, 0x6f
	v_cmp_lt_u32_e64 s[12:13], s10, v3
	v_mul_u32_u24_e32 v8, 0x61200, v1
	v_lshlrev_b32_e32 v10, 11, v0
	v_lshl_add_u32 v10, v1, 4, v10
	v_cndmask_b32_e64 v4, 0, -1, s[12:13]
	v_cndmask_b32_e64 v2, 0, v2, s[12:13]
	v_mov_b32_e32 v9, 0
	v_mov_b32_e32 v11, 0
	v_lshl_add_u32 v8, v2, 2, v8
	s_mov_b64 s[14:15], 0xc240
	v_lshl_add_u64 v[8:9], v[8:9], 0, s[4:5]
	v_lshl_add_u64 v[10:11], v[10:11], 0, s[6:7]
	s_mov_b64 s[34:35], 0x1000
	global_load_dwordx4 v[16:19], v[8:9], off
	v_lshl_add_u64 v[8:9], v[8:9], 0, s[14:15]
	global_load_dwordx4 v[20:23], v[8:9], off
	v_lshl_add_u64 v[8:9], v[8:9], 0, s[14:15]
	global_load_dwordx4 v[24:27], v[8:9], off
	v_lshl_add_u64 v[8:9], v[8:9], 0, s[14:15]
	global_load_dwordx4 v[28:31], v[8:9], off
	v_lshl_add_u64 v[8:9], v[8:9], 0, s[14:15]
	global_load_dwordx4 v[32:35], v[8:9], off
	v_lshl_add_u64 v[8:9], v[8:9], 0, s[14:15]
	global_load_dwordx4 v[36:39], v[8:9], off
	v_lshl_add_u64 v[8:9], v[8:9], 0, s[14:15]
	global_load_dwordx4 v[40:43], v[8:9], off
	v_lshl_add_u64 v[8:9], v[8:9], 0, s[14:15]
	global_load_dwordx4 v[44:47], v[8:9], off
	v_lshl_add_u64 v[12:13], v[10:11], 0, s[34:35]
	v_add_u32_e32 v6, s2, v6
	s_mov_b32 s10, 0x61fff
	v_cmp_lt_i32_e32 vcc, s10, v6
	s_nop 1
	s_or_b64 s[8:9], vcc, s[8:9]
	s_waitcnt vmcnt(7)
	v_bfe_u32 v14, v16, 16, 1
	v_add3_u32 v16, v16, v14, s33
	v_bfe_u32 v15, v17, 16, 1
	v_add3_u32 v17, v17, v15, s33
	v_bfe_u32 v14, v18, 16, 1
	v_add3_u32 v18, v18, v14, s33
	v_bfe_u32 v15, v19, 16, 1
	v_add3_u32 v19, v19, v15, s33
	s_waitcnt vmcnt(6)
	v_bfe_u32 v14, v20, 16, 1
	v_add3_u32 v20, v20, v14, s33
	v_bfe_u32 v15, v21, 16, 1
	v_add3_u32 v21, v21, v15, s33
	v_bfe_u32 v14, v22, 16, 1
	v_add3_u32 v22, v22, v14, s33
	v_bfe_u32 v15, v23, 16, 1
	v_add3_u32 v23, v23, v15, s33
	s_waitcnt vmcnt(5)
	v_bfe_u32 v14, v24, 16, 1
	v_add3_u32 v24, v24, v14, s33
	v_bfe_u32 v15, v25, 16, 1
	v_add3_u32 v25, v25, v15, s33
	v_bfe_u32 v14, v26, 16, 1
	v_add3_u32 v26, v26, v14, s33
	v_bfe_u32 v15, v27, 16, 1
	v_add3_u32 v27, v27, v15, s33
	s_waitcnt vmcnt(4)
	v_bfe_u32 v14, v28, 16, 1
	v_add3_u32 v28, v28, v14, s33
	v_bfe_u32 v15, v29, 16, 1
	v_add3_u32 v29, v29, v15, s33
	v_bfe_u32 v14, v30, 16, 1
	v_add3_u32 v30, v30, v14, s33
	v_bfe_u32 v15, v31, 16, 1
	v_add3_u32 v31, v31, v15, s33
	s_waitcnt vmcnt(3)
	v_bfe_u32 v14, v32, 16, 1
	v_add3_u32 v32, v32, v14, s33
	v_bfe_u32 v15, v33, 16, 1
	v_add3_u32 v33, v33, v15, s33
	v_bfe_u32 v14, v34, 16, 1
	v_add3_u32 v34, v34, v14, s33
	v_bfe_u32 v15, v35, 16, 1
	v_add3_u32 v35, v35, v15, s33
	s_waitcnt vmcnt(2)
	v_bfe_u32 v14, v36, 16, 1
	v_add3_u32 v36, v36, v14, s33
	v_bfe_u32 v15, v37, 16, 1
	v_add3_u32 v37, v37, v15, s33
	v_bfe_u32 v14, v38, 16, 1
	v_add3_u32 v38, v38, v14, s33
	v_bfe_u32 v15, v39, 16, 1
	v_add3_u32 v39, v39, v15, s33
	s_waitcnt vmcnt(1)
	v_bfe_u32 v14, v40, 16, 1
	v_add3_u32 v40, v40, v14, s33
	v_bfe_u32 v15, v41, 16, 1
	v_add3_u32 v41, v41, v15, s33
	v_bfe_u32 v14, v42, 16, 1
	v_add3_u32 v42, v42, v14, s33
	v_bfe_u32 v15, v43, 16, 1
	v_add3_u32 v43, v43, v15, s33
	s_waitcnt vmcnt(0)
	v_bfe_u32 v14, v44, 16, 1
	v_add3_u32 v44, v44, v14, s33
	v_bfe_u32 v15, v45, 16, 1
	v_add3_u32 v45, v45, v15, s33
	v_bfe_u32 v14, v46, 16, 1
	v_add3_u32 v46, v46, v14, s33
	v_bfe_u32 v15, v47, 16, 1
	v_add3_u32 v47, v47, v15, s33
	v_perm_b32 v48, v20, v16, s96
	v_perm_b32 v49, v28, v24, s96
	v_perm_b32 v50, v36, v32, s96
	v_perm_b32 v51, v44, v40, s96
	v_perm_b32 v52, v21, v17, s96
	v_perm_b32 v53, v29, v25, s96
	v_perm_b32 v54, v37, v33, s96
	v_perm_b32 v55, v45, v41, s96
	v_perm_b32 v56, v22, v18, s96
	v_perm_b32 v57, v30, v26, s96
	v_perm_b32 v58, v38, v34, s96
	v_perm_b32 v59, v46, v42, s96
	v_perm_b32 v60, v23, v19, s96
	v_perm_b32 v61, v31, v27, s96
	v_perm_b32 v62, v39, v35, s96
	v_perm_b32 v63, v47, v43, s96
	v_and_b32_e32 v48, v48, v4
	v_and_b32_e32 v49, v49, v4
	v_and_b32_e32 v50, v50, v4
	v_and_b32_e32 v51, v51, v4
	v_and_b32_e32 v52, v52, v4
	v_and_b32_e32 v53, v53, v4
	v_and_b32_e32 v54, v54, v4
	v_and_b32_e32 v55, v55, v4
	v_and_b32_e32 v56, v56, v4
	v_and_b32_e32 v57, v57, v4
	v_and_b32_e32 v58, v58, v4
	v_and_b32_e32 v59, v59, v4
	v_and_b32_e32 v60, v60, v4
	v_and_b32_e32 v61, v61, v4
	v_and_b32_e32 v62, v62, v4
	v_and_b32_e32 v63, v63, v4
	global_store_dwordx4 v[10:11], v[48:51], off
	global_store_dwordx4 v[10:11], v[52:55], off offset:2048
	global_store_dwordx4 v[12:13], v[56:59], off
	global_store_dwordx4 v[12:13], v[60:63], off offset:2048
	s_andn2_b64 exec, exec, s[8:9]
	s_cbranch_execnz .LBB0_630
